# grid barrier: first workgroup of each XCD to arrive starts an early L2 write-back (on top of two-level publishes)
# baseline (speedup 1.0000x reference)
; DI unsigned xb_ld(unsigned* p)              { return __hip_atomic_load(p, __ATOMIC_RELAXED, __HIP_MEMORY_SCOPE_AGENT); }
; DI unsigned xb_add(unsigned* p, unsigned v) { return __hip_atomic_fetch_add(p, v, __ATOMIC_RELAXED, __HIP_MEMORY_SCOPE_AGENT); }
; #define XB_SPIN(cond, bar) do { unsigned _sp = 0; while (cond) { __builtin_amdgcn_s_sleep(1); \
;     if ((++_sp & 255u) == 0u) { if (xb_ld(&(bar)[XB_TMO])) break; if (_sp > XB_SPIN_CAP) { atomicAdd(&(bar)[XB_TMO], 1u); break; } } } } while (0)
; DI void xcd_barrier(unsigned* bar, volatile LAS unsigned* st, bool leader) {
;     ...
;         const unsigned old = xb_add(&bar[XB_XSUB(x)], 1u);
;         const unsigned gen = old / nloc;
;         if (old + 1u == (gen + 1u) * nloc) {
;     ...
;             XB_SPIN(xb_ld(&bar[XB_XGEN(x)]) == gen, bar);
.LBB0_195:
	s_or_b64 exec, exec, s[8:9]
	v_cvt_f32_u32_e32 v4, v2
	s_waitcnt vmcnt(0)
	v_readfirstlane_b32 s6, v3
	v_sub_u32_e32 v3, 0, v2
	v_rcp_iflag_f32_e32 v4, v4
	v_add_u32_e32 v5, s6, v1
	v_mul_f32_e32 v4, 0x4f7ffffe, v4
	v_cvt_u32_f32_e32 v4, v4
	v_mul_lo_u32 v1, v3, v4
	v_mul_hi_u32 v1, v4, v1
	v_add_u32_e32 v1, v4, v1
	v_mul_hi_u32 v1, v5, v1
	v_mul_lo_u32 v3, v1, v2
	v_sub_u32_e32 v3, v5, v3
	v_add_u32_e32 v4, 1, v1
	v_cmp_ge_u32_e32 vcc, v3, v2
	s_nop 1
	v_cndmask_b32_e32 v1, v1, v4, vcc
	v_sub_u32_e32 v4, v3, v2
	v_cndmask_b32_e32 v3, v3, v4, vcc
	v_add_u32_e32 v4, 1, v1
	v_cmp_ge_u32_e32 vcc, v3, v2
	v_add_u32_e32 v3, 1, v5
	s_nop 0
	v_cndmask_b32_e32 v1, v1, v4, vcc
	v_mul_lo_u32 v4, v2, v1
	v_cmp_eq_u32_e64 s[8:9], v5, v4
	s_and_b64 s[8:9], s[8:9], exec
	s_cbranch_scc0 .Lewb_0
	buffer_wbl2 sc1
.Lewb_0:
	v_add_u32_e32 v2, v4, v2
	v_cmp_ne_u32_e32 vcc, v3, v2
	s_and_saveexec_b64 s[6:7], vcc
	s_xor_b64 s[6:7], exec, s[6:7]
	s_cbranch_execz .LBB0_209
	s_waitcnt lgkmcnt(0)
	v_mov_b32_e32 v0, 0x2000
	global_load_dword v0, v0, s[4:5] offset:1024 sc1
	s_add_u32 s10, s4, 0x2400
	s_addc_u32 s11, s5, 0
	s_waitcnt vmcnt(0)
	v_cmp_eq_u32_e32 vcc, v0, v1
	s_and_saveexec_b64 s[8:9], vcc
	s_cbranch_execz .LBB0_208
	s_mov_b32 s14, 1
	s_mov_b64 s[12:13], 0
	v_mov_b32_e32 v0, 0
	s_branch .LBB0_199

; DI unsigned xb_ld(unsigned* p)              { return __hip_atomic_load(p, __ATOMIC_RELAXED, __HIP_MEMORY_SCOPE_AGENT); }
; #define XB_SPIN(cond, bar) do { unsigned _sp = 0; while (cond) { __builtin_amdgcn_s_sleep(1); \
;     if ((++_sp & 255u) == 0u) { if (xb_ld(&(bar)[XB_TMO])) break; if (_sp > XB_SPIN_CAP) { atomicAdd(&(bar)[XB_TMO], 1u); break; } } } } while (0)
; DI void xcd_barrier(unsigned* bar, volatile LAS unsigned* st, bool leader) {
;     ...
;         if (old + 1u == (gen + 1u) * nloc) {
;     ...
;         } else {
;             XB_SPIN(xb_ld(&bar[XB_XGEN(x)]) == gen, bar);
.Lewb_2:
	v_add_u32_e32 v2, v4, v2
	v_cmp_ne_u32_e32 vcc, v3, v2
	s_and_saveexec_b64 s[6:7], vcc
	s_xor_b64 s[6:7], exec, s[6:7]
	s_cbranch_execz .LBB0_631
	s_waitcnt lgkmcnt(0)
	v_mov_b32_e32 v0, 0x2000
	global_load_dword v0, v0, s[4:5] offset:1024 sc1
	s_add_u32 s10, s4, 0x2400
	s_addc_u32 s11, s5, 0
	s_waitcnt vmcnt(0)
	v_cmp_eq_u32_e32 vcc, v0, v1
	s_and_saveexec_b64 s[8:9], vcc
	s_cbranch_execz .LBB0_630
	s_mov_b32 s22, 1
	s_mov_b64 s[12:13], 0
	s_branch .LBB0_621
